# grid.sync 2..9 replaced by hierarchical 8-group monotonic atomic-counter barrier in d_ws
# speedup vs baseline: 1.0223x; 1.0223x over previous
; DI void phase0(const Params& p, char* lds) {
;     ...
;   if (blockIdx.x == 0 && threadIdx.x < 64) {
;     const int t = threadIdx.x;
;     float a = p.in[15][t] * p.in[16][t] + p.in[15][t + 64] * p.in[16][t + 64];
;     float b = p.in[17][t] * p.in[18][t] + p.in[17][t + 64] * p.in[18][t + 64];
;     float gq = fmaxf(fabsf(p.in[13][t]), fabsf(p.in[13][t + 64])), gk = fmaxf(fabsf(p.in[14][t]), fabsf(p.in[14][t + 64]));
;     for (int o = 32; o > 0; o >>= 1) { a += __shfl_xor(a, o); b += __shfl_xor(b, o); gq = fmaxf(gq, __shfl_xor(gq, o)); gk = fmaxf(gk, __shfl_xor(gk, o)); }
;     if (t == 0) {
;       float* lt = (float*)(ws + OFF_LAM);
;       const float lam_init = 0.8f - 0.6f * expf(-0.3f * 1.0f);
;       lt[0] = expf(a) - expf(b) + lam_init; lt[1] = lam_init;
;       lt[2] = 150.0f + 2.0f * (11.313708499f * gq * gk * LOG2E * 1.03f);
;       lt[4] = 11.313708499f * gq * gk * LOG2E * 1.03f;
;       ((int*)lt)[8] = 0;
;     }
;   }
.LBB0_144:
	s_or_b64 exec, exec, s[0:1]
	v_cmp_gt_u32_e32 vcc, 64, v208
	s_and_b64 s[4:5], s[6:7], vcc
	s_and_saveexec_b64 s[0:1], s[4:5]
	s_cbranch_execz .LBB0_147
	global_load_dword v1, v2, s[40:41] offset:256
	s_waitcnt lgkmcnt(1)
	global_load_dword v3, v2, s[42:43] offset:256
	global_load_dword v4, v2, s[44:45] offset:256
	s_waitcnt lgkmcnt(0)
	global_load_dword v5, v2, s[40:41]
	global_load_dword v6, v2, s[30:31] offset:256
	global_load_dword v7, v2, s[42:43]
	global_load_dword v8, v2, s[26:27] offset:256
	global_load_dword v9, v2, s[26:27]
	global_load_dword v10, v2, s[28:29] offset:256
	global_load_dword v11, v2, s[28:29]
	global_load_dword v12, v2, s[30:31]
	s_nop 0
	global_load_dword v2, v2, s[44:45]
	v_mbcnt_hi_u32_b32 v13, -1, v210
	v_and_b32_e32 v14, 64, v13
	v_xor_b32_e32 v15, 32, v13
	v_add_u32_e32 v14, 64, v14
	v_xor_b32_e32 v16, 16, v13
	v_cmp_lt_i32_e32 vcc, v15, v14
	v_xor_b32_e32 v17, 8, v13
	v_xor_b32_e32 v18, 4, v13
	v_cndmask_b32_e32 v15, v13, v15, vcc
	v_cmp_lt_i32_e32 vcc, v16, v14
	v_xor_b32_e32 v19, 2, v13
	v_xor_b32_e32 v20, 1, v13
	v_cndmask_b32_e32 v16, v13, v16, vcc
	v_cmp_lt_i32_e32 vcc, v17, v14
	s_waitcnt vmcnt(9)
	v_mul_f32_e32 v3, v3, v4
	v_cndmask_b32_e32 v17, v13, v17, vcc
	v_cmp_lt_i32_e32 vcc, v18, v14
	s_waitcnt vmcnt(7)
	v_mul_f32_e32 v1, v6, v1
	s_waitcnt vmcnt(5)
	v_max_f32_e64 v4, |v8|, |v8|
	v_cndmask_b32_e32 v18, v13, v18, vcc
	v_cmp_lt_i32_e32 vcc, v19, v14
	s_waitcnt vmcnt(4)
	v_max_f32_e64 v6, |v9|, |v9|
	s_waitcnt vmcnt(3)
	v_max_f32_e64 v8, |v10|, |v10|
	s_waitcnt vmcnt(2)
	v_max_f32_e64 v9, |v11|, |v11|
	v_cndmask_b32_e32 v19, v13, v19, vcc
	v_cmp_lt_i32_e32 vcc, v20, v14
	v_lshlrev_b32_e32 v14, 2, v15
	s_waitcnt vmcnt(1)
	v_fmac_f32_e32 v1, v12, v5
	s_waitcnt vmcnt(0)
	v_fmac_f32_e32 v3, v7, v2
	v_max_f32_e32 v2, v6, v4
	v_max_f32_e32 v4, v9, v8
	ds_bpermute_b32 v5, v14, v1
	ds_bpermute_b32 v6, v14, v3
	ds_bpermute_b32 v7, v14, v2
	ds_bpermute_b32 v8, v14, v4
	v_lshlrev_b32_e32 v15, 2, v16
	s_waitcnt lgkmcnt(3)
	v_add_f32_e32 v1, v1, v5
	s_waitcnt lgkmcnt(2)
	v_add_f32_e32 v3, v3, v6
	s_waitcnt lgkmcnt(1)
	v_max_f32_e32 v5, v7, v7
	s_waitcnt lgkmcnt(0)
	v_max_f32_e32 v6, v8, v8
	v_max_f32_e32 v2, v2, v5
	v_max_f32_e32 v4, v4, v6
	ds_bpermute_b32 v5, v15, v1
	ds_bpermute_b32 v6, v15, v3
	ds_bpermute_b32 v7, v15, v2
	ds_bpermute_b32 v8, v15, v4
	v_lshlrev_b32_e32 v16, 2, v17
	s_waitcnt lgkmcnt(3)
	v_add_f32_e32 v1, v1, v5
	s_waitcnt lgkmcnt(2)
	v_add_f32_e32 v3, v3, v6
	s_waitcnt lgkmcnt(1)
	v_max_f32_e32 v5, v7, v7
	s_waitcnt lgkmcnt(0)
	v_max_f32_e32 v6, v8, v8
	v_max_f32_e32 v2, v2, v5
	v_max_f32_e32 v4, v4, v6
	ds_bpermute_b32 v5, v16, v2
	ds_bpermute_b32 v6, v16, v4
	ds_bpermute_b32 v7, v16, v1
	ds_bpermute_b32 v8, v16, v3
	v_lshlrev_b32_e32 v17, 2, v18
	s_waitcnt lgkmcnt(3)
	v_max_f32_e32 v5, v5, v5
	s_waitcnt lgkmcnt(2)
	v_max_f32_e32 v6, v6, v6
	v_max_f32_e32 v2, v2, v5
	v_max_f32_e32 v4, v4, v6
	s_waitcnt lgkmcnt(1)
	v_add_f32_e32 v1, v1, v7
	s_waitcnt lgkmcnt(0)
	v_add_f32_e32 v3, v3, v8
	ds_bpermute_b32 v5, v17, v2
	ds_bpermute_b32 v6, v17, v4
	ds_bpermute_b32 v7, v17, v1
	ds_bpermute_b32 v8, v17, v3
	v_lshlrev_b32_e32 v9, 2, v19
	s_waitcnt lgkmcnt(3)
	v_max_f32_e32 v5, v5, v5
	s_waitcnt lgkmcnt(2)
	v_max_f32_e32 v6, v6, v6
	s_waitcnt lgkmcnt(1)
	v_add_f32_e32 v1, v1, v7
	s_waitcnt lgkmcnt(0)
	v_add_f32_e32 v3, v3, v8
	v_max_f32_e32 v11, v2, v5
	v_max_f32_e32 v6, v4, v6
	ds_bpermute_b32 v7, v9, v1
	ds_bpermute_b32 v8, v9, v3
	ds_bpermute_b32 v12, v9, v11
	ds_bpermute_b32 v9, v9, v6
	v_cndmask_b32_e32 v13, v13, v20, vcc
	s_waitcnt lgkmcnt(3)
	v_add_f32_e32 v4, v1, v7
	s_waitcnt lgkmcnt(2)
	v_add_f32_e32 v1, v3, v8
	s_waitcnt lgkmcnt(1)
	v_max_f32_e32 v3, v12, v12
	s_waitcnt lgkmcnt(0)
	v_max_f32_e32 v7, v9, v9
	v_lshlrev_b32_e32 v10, 2, v13
	v_max_f32_e32 v3, v11, v3
	v_max_f32_e32 v7, v6, v7
	ds_bpermute_b32 v5, v10, v4
	ds_bpermute_b32 v2, v10, v1
	ds_bpermute_b32 v6, v10, v3
	ds_bpermute_b32 v8, v10, v7
	v_cmp_eq_u32_e32 vcc, 0, v208
	s_and_b64 exec, exec, vcc
	s_cbranch_execz .LBB0_147
	s_waitcnt lgkmcnt(3)
	v_add_f32_e32 v4, v4, v5
	s_waitcnt lgkmcnt(0)
	v_max_f32_e32 v8, v8, v8
	v_max_f32_e32 v7, v7, v7
	s_mov_b32 s3, 0x3fb8aa3b
	v_mul_f32_e32 v5, 0x3fb8aa3b, v4
	v_max_f32_e32 v7, v7, v8
	v_fma_f32 v8, v4, s3, -v5
	v_rndne_f32_e32 v9, v5
	v_fmac_f32_e32 v8, 0x32a5705f, v4
	v_sub_f32_e32 v5, v5, v9
	v_add_f32_e32 v5, v5, v8
	v_exp_f32_e32 v5, v5
	v_cvt_i32_f32_e32 v8, v9
	v_add_f32_e32 v1, v1, v2
	v_max_f32_e32 v6, v6, v6
	v_max_f32_e32 v3, v3, v3
	v_ldexp_f32 v2, v5, v8
	v_mul_f32_e32 v5, 0x3fb8aa3b, v1
	v_max_f32_e32 v3, v3, v6
	v_fma_f32 v6, v1, s3, -v5
	v_rndne_f32_e32 v8, v5
	v_fmac_f32_e32 v6, 0x32a5705f, v1
	v_sub_f32_e32 v5, v5, v8
	v_add_f32_e32 v5, v5, v6
	v_exp_f32_e32 v5, v5
	v_cvt_i32_f32_e32 v6, v8
	s_mov_b32 s4, 0xc2ce8ed0
	v_cmp_ngt_f32_e32 vcc, s4, v4
	s_mov_b32 s5, 0x42b17218
	v_mov_b32_e32 v8, 0x7f800000
	v_cndmask_b32_e32 v2, 0, v2, vcc
	v_cmp_nlt_f32_e32 vcc, s5, v4
	v_ldexp_f32 v4, v5, v6
	v_mov_b32_e32 v5, 0x4808000
	v_cndmask_b32_e32 v2, v8, v2, vcc
	v_cmp_ngt_f32_e32 vcc, s4, v1
	s_nop 1
	v_cndmask_b32_e32 v4, 0, v4, vcc
	v_cmp_nlt_f32_e32 vcc, s5, v1
	s_nop 1
	v_cndmask_b32_e32 v1, v8, v4, vcc
	v_sub_f32_e32 v1, v2, v1
	v_add_f32_e32 v2, 0x3eb60549, v1
	v_mul_f32_e32 v1, 0x413504f3, v3
	v_mul_f32_e32 v1, v1, v7
	v_mul_f32_e32 v1, 0x3fb8aa3b, v1
	v_mul_f32_e32 v1, 0x3f83d70a, v1
	v_fmaak_f32 v4, 2.0, v1, 0x43160000
	v_mov_b32_e32 v3, 0x3eb60549
	global_store_dwordx3 v5, v[2:4], s[56:57]
	global_store_dword v5, v1, s[56:57] offset:16
	v_mov_b32_e32 v1, 0
	global_store_dword v5, v1, s[56:57] offset:32
	v_mov_b32_e32 v6, 0x4807800
	global_atomic_and v6, v1, s[56:57]
	global_atomic_and v6, v1, s[56:57] offset:128
	global_atomic_and v6, v1, s[56:57] offset:256
	global_atomic_and v6, v1, s[56:57] offset:384
	global_atomic_and v6, v1, s[56:57] offset:512
	global_atomic_and v6, v1, s[56:57] offset:640
	global_atomic_and v6, v1, s[56:57] offset:768
	global_atomic_and v6, v1, s[56:57] offset:896
	global_atomic_and v6, v1, s[56:57] offset:1024
	global_atomic_and v6, v1, s[56:57] offset:1152
	global_atomic_and v6, v1, s[56:57] offset:1280
	global_atomic_and v6, v1, s[56:57] offset:1408
	global_atomic_and v6, v1, s[56:57] offset:1536
	global_atomic_and v6, v1, s[56:57] offset:1664
	global_atomic_and v6, v1, s[56:57] offset:1792
	global_atomic_and v6, v1, s[56:57] offset:1920

; __global__ void __launch_bounds__(512) mega_fwd(Params p) {
;     ...
;   grid.sync();
.LBB0_235:
	s_waitcnt vmcnt(0) lgkmcnt(0)
	s_barrier
	s_and_saveexec_b64 s[4:5], s[94:95]
	s_cbranch_execz .LBB0_245
	buffer_wbl2 sc1
	s_waitcnt vmcnt(0)
	s_sub_u32 s8, s92, 8
	s_subb_u32 s9, s93, 0
	s_load_dword s10, s[92:93], 0x0
	s_load_dwordx2 s[8:9], s[8:9], 0x0
	s_and_b32 s0, s2, 7
	s_lshl_b32 s1, s0, 7
	s_add_i32 s1, s1, 0x4807800
	v_mov_b32_e32 v0, s1
	v_mov_b32_e32 v1, 1
	v_mov_b32_e32 v3, 0
	s_waitcnt lgkmcnt(0)
	global_atomic_add v2, v0, v1, s[8:9] sc0
	s_min_u32 s11, s10, 8
	s_mul_i32 s11, s11, 1
	s_sub_i32 s10, s10, s0
	s_add_i32 s10, s10, 7
	s_lshr_b32 s10, s10, 3
	s_mul_i32 s10, s10, 1
	s_mov_b32 s12, 0x8000
	v_add_u32_e32 v0, 0x400, v0
	s_waitcnt vmcnt(0)
	v_readfirstlane_b32 s0, v2
	s_nop 0
	s_add_i32 s0, s0, 1
	s_cmp_lg_u32 s0, s10
	s_cbranch_scc1 .Lgsync_spin_1
	v_mov_b32_e32 v2, 0x4807c00
	global_atomic_add v2, v1, s[8:9]
	global_atomic_add v2, v1, s[8:9] offset:128
	global_atomic_add v2, v1, s[8:9] offset:256
	global_atomic_add v2, v1, s[8:9] offset:384
	global_atomic_add v2, v1, s[8:9] offset:512
	global_atomic_add v2, v1, s[8:9] offset:640
	global_atomic_add v2, v1, s[8:9] offset:768
	global_atomic_add v2, v1, s[8:9] offset:896
.Lgsync_spin_1:
	global_atomic_add v2, v0, v3, s[8:9] sc0
	s_waitcnt vmcnt(0)
	v_readfirstlane_b32 s0, v2
	s_nop 0
	s_cmp_ge_u32 s0, s11
	s_cbranch_scc1 .Lgsync_done_1
	s_add_i32 s12, s12, -1
	s_cmp_eq_u32 s12, 0
	s_cbranch_scc1 .Lgsync_done_1
	s_sleep 1
	s_branch .Lgsync_spin_1

; __global__ void __launch_bounds__(512) mega_fwd(Params p) {
;     ...
;   grid.sync();
.LBB0_303:
	s_waitcnt vmcnt(0) lgkmcnt(0)
	s_barrier
	s_and_saveexec_b64 s[8:9], s[94:95]
	v_readlane_b32 s22, v254, 2
	s_cbranch_execz .LBB0_313
	buffer_wbl2 sc1
	s_waitcnt vmcnt(0)
	s_sub_u32 s10, s92, 8
	s_subb_u32 s11, s93, 0
	s_load_dword s12, s[92:93], 0x0
	s_load_dwordx2 s[10:11], s[10:11], 0x0
	s_and_b32 s0, s2, 7
	s_lshl_b32 s1, s0, 7
	s_add_i32 s1, s1, 0x4807800
	v_mov_b32_e32 v0, s1
	v_mov_b32_e32 v1, 1
	v_mov_b32_e32 v3, 0
	s_waitcnt lgkmcnt(0)
	global_atomic_add v2, v0, v1, s[10:11] sc0
	s_min_u32 s13, s12, 8
	s_mul_i32 s13, s13, 2
	s_sub_i32 s12, s12, s0
	s_add_i32 s12, s12, 7
	s_lshr_b32 s12, s12, 3
	s_mul_i32 s12, s12, 2
	s_mov_b32 s44, 0x8000
	v_add_u32_e32 v0, 0x400, v0
	s_waitcnt vmcnt(0)
	v_readfirstlane_b32 s0, v2
	s_nop 0
	s_add_i32 s0, s0, 1
	s_cmp_lg_u32 s0, s12
	s_cbranch_scc1 .Lgsync_spin_2
	v_mov_b32_e32 v2, 0x4807c00
	global_atomic_add v2, v1, s[10:11]
	global_atomic_add v2, v1, s[10:11] offset:128
	global_atomic_add v2, v1, s[10:11] offset:256
	global_atomic_add v2, v1, s[10:11] offset:384
	global_atomic_add v2, v1, s[10:11] offset:512
	global_atomic_add v2, v1, s[10:11] offset:640
	global_atomic_add v2, v1, s[10:11] offset:768
	global_atomic_add v2, v1, s[10:11] offset:896
.Lgsync_spin_2:
	global_atomic_add v2, v0, v3, s[10:11] sc0
	s_waitcnt vmcnt(0)
	v_readfirstlane_b32 s0, v2
	s_nop 0
	s_cmp_ge_u32 s0, s13
	s_cbranch_scc1 .Lgsync_done_2
	s_add_i32 s44, s44, -1
	s_cmp_eq_u32 s44, 0
	s_cbranch_scc1 .Lgsync_done_2
	s_sleep 1
	s_branch .Lgsync_spin_2

; __global__ void __launch_bounds__(512) mega_fwd(Params p) {
;     ...
;   grid.sync();
.LBB0_353:
	s_or_b64 exec, exec, s[68:69]
	s_waitcnt vmcnt(0) lgkmcnt(0)
	s_barrier
	s_and_saveexec_b64 s[8:9], s[94:95]
	s_cbranch_execz .LBB0_363
	buffer_wbl2 sc1
	s_waitcnt vmcnt(0)
	s_sub_u32 s10, s92, 8
	s_subb_u32 s11, s93, 0
	s_load_dword s12, s[92:93], 0x0
	s_load_dwordx2 s[10:11], s[10:11], 0x0
	s_and_b32 s0, s2, 7
	s_lshl_b32 s1, s0, 7
	s_add_i32 s1, s1, 0x4807800
	v_mov_b32_e32 v0, s1
	v_mov_b32_e32 v1, 1
	v_mov_b32_e32 v3, 0
	s_waitcnt lgkmcnt(0)
	global_atomic_add v2, v0, v1, s[10:11] sc0
	s_min_u32 s13, s12, 8
	s_mul_i32 s13, s13, 3
	s_sub_i32 s12, s12, s0
	s_add_i32 s12, s12, 7
	s_lshr_b32 s12, s12, 3
	s_mul_i32 s12, s12, 3
	s_mov_b32 s16, 0x8000
	v_add_u32_e32 v0, 0x400, v0
	s_waitcnt vmcnt(0)
	v_readfirstlane_b32 s0, v2
	s_nop 0
	s_add_i32 s0, s0, 1
	s_cmp_lg_u32 s0, s12
	s_cbranch_scc1 .Lgsync_spin_3
	v_mov_b32_e32 v2, 0x4807c00
	global_atomic_add v2, v1, s[10:11]
	global_atomic_add v2, v1, s[10:11] offset:128
	global_atomic_add v2, v1, s[10:11] offset:256
	global_atomic_add v2, v1, s[10:11] offset:384
	global_atomic_add v2, v1, s[10:11] offset:512
	global_atomic_add v2, v1, s[10:11] offset:640
	global_atomic_add v2, v1, s[10:11] offset:768
	global_atomic_add v2, v1, s[10:11] offset:896
.Lgsync_spin_3:
	global_atomic_add v2, v0, v3, s[10:11] sc0
	s_waitcnt vmcnt(0)
	v_readfirstlane_b32 s0, v2
	s_nop 0
	s_cmp_ge_u32 s0, s13
	s_cbranch_scc1 .Lgsync_done_3
	s_add_i32 s16, s16, -1
	s_cmp_eq_u32 s16, 0
	s_cbranch_scc1 .Lgsync_done_3
	s_sleep 1
	s_branch .Lgsync_spin_3

; __global__ void __launch_bounds__(512) mega_fwd(Params p) {
;     ...
;   grid.sync();
.LBB0_407:
	s_waitcnt vmcnt(0)
	s_barrier
	s_and_saveexec_b64 s[8:9], s[94:95]
	s_cbranch_execz .LBB0_417
	buffer_wbl2 sc1
	s_waitcnt vmcnt(0)
	s_sub_u32 s10, s92, 8
	s_subb_u32 s11, s93, 0
	s_load_dword s12, s[92:93], 0x0
	s_load_dwordx2 s[10:11], s[10:11], 0x0
	s_and_b32 s0, s2, 7
	s_lshl_b32 s1, s0, 7
	s_add_i32 s1, s1, 0x4807800
	v_mov_b32_e32 v0, s1
	v_mov_b32_e32 v1, 1
	v_mov_b32_e32 v3, 0
	s_waitcnt lgkmcnt(0)
	global_atomic_add v2, v0, v1, s[10:11] sc0
	s_min_u32 s13, s12, 8
	s_mul_i32 s13, s13, 4
	s_sub_i32 s12, s12, s0
	s_add_i32 s12, s12, 7
	s_lshr_b32 s12, s12, 3
	s_mul_i32 s12, s12, 4
	s_mov_b32 s14, 0x8000
	v_add_u32_e32 v0, 0x400, v0
	s_waitcnt vmcnt(0)
	v_readfirstlane_b32 s0, v2
	s_nop 0
	s_add_i32 s0, s0, 1
	s_cmp_lg_u32 s0, s12
	s_cbranch_scc1 .Lgsync_spin_4
	v_mov_b32_e32 v2, 0x4807c00
	global_atomic_add v2, v1, s[10:11]
	global_atomic_add v2, v1, s[10:11] offset:128
	global_atomic_add v2, v1, s[10:11] offset:256
	global_atomic_add v2, v1, s[10:11] offset:384
	global_atomic_add v2, v1, s[10:11] offset:512
	global_atomic_add v2, v1, s[10:11] offset:640
	global_atomic_add v2, v1, s[10:11] offset:768
	global_atomic_add v2, v1, s[10:11] offset:896
.Lgsync_spin_4:
	global_atomic_add v2, v0, v3, s[10:11] sc0
	s_waitcnt vmcnt(0)
	v_readfirstlane_b32 s0, v2
	s_nop 0
	s_cmp_ge_u32 s0, s13
	s_cbranch_scc1 .Lgsync_done_4
	s_add_i32 s14, s14, -1
	s_cmp_eq_u32 s14, 0
	s_cbranch_scc1 .Lgsync_done_4
	s_sleep 1
	s_branch .Lgsync_spin_4

; __global__ void __launch_bounds__(512) mega_fwd(Params p) {
;     ...
;   grid.sync();
.LBB0_455:
	s_waitcnt vmcnt(0) lgkmcnt(0)
	s_barrier
	s_and_saveexec_b64 s[8:9], s[94:95]
	s_cbranch_execz .LBB0_465
	buffer_wbl2 sc1
	s_waitcnt vmcnt(0)
	s_sub_u32 s10, s92, 8
	s_subb_u32 s11, s93, 0
	s_load_dword s12, s[92:93], 0x0
	s_load_dwordx2 s[10:11], s[10:11], 0x0
	s_and_b32 s0, s2, 7
	s_lshl_b32 s1, s0, 7
	s_add_i32 s1, s1, 0x4807800
	v_mov_b32_e32 v0, s1
	v_mov_b32_e32 v1, 1
	v_mov_b32_e32 v3, 0
	s_waitcnt lgkmcnt(0)
	global_atomic_add v2, v0, v1, s[10:11] sc0
	s_min_u32 s13, s12, 8
	s_mul_i32 s13, s13, 5
	s_sub_i32 s12, s12, s0
	s_add_i32 s12, s12, 7
	s_lshr_b32 s12, s12, 3
	s_mul_i32 s12, s12, 5
	s_mov_b32 s14, 0x8000
	v_add_u32_e32 v0, 0x400, v0
	s_waitcnt vmcnt(0)
	v_readfirstlane_b32 s0, v2
	s_nop 0
	s_add_i32 s0, s0, 1
	s_cmp_lg_u32 s0, s12
	s_cbranch_scc1 .Lgsync_spin_5
	v_mov_b32_e32 v2, 0x4807c00
	global_atomic_add v2, v1, s[10:11]
	global_atomic_add v2, v1, s[10:11] offset:128
	global_atomic_add v2, v1, s[10:11] offset:256
	global_atomic_add v2, v1, s[10:11] offset:384
	global_atomic_add v2, v1, s[10:11] offset:512
	global_atomic_add v2, v1, s[10:11] offset:640
	global_atomic_add v2, v1, s[10:11] offset:768
	global_atomic_add v2, v1, s[10:11] offset:896

; __global__ void __launch_bounds__(512) mega_fwd(Params p) {
;     ...
;   grid.sync();
.LBB0_525:
	s_waitcnt vmcnt(0) lgkmcnt(0)
	s_barrier
	s_and_saveexec_b64 s[6:7], s[94:95]
	s_cbranch_execz .LBB0_535
	buffer_wbl2 sc1
	s_waitcnt vmcnt(0)
	s_sub_u32 s8, s92, 8
	s_subb_u32 s9, s93, 0
	s_load_dword s10, s[92:93], 0x0
	s_load_dwordx2 s[8:9], s[8:9], 0x0
	s_and_b32 s0, s2, 7
	s_lshl_b32 s1, s0, 7
	s_add_i32 s1, s1, 0x4807800
	v_mov_b32_e32 v0, s1
	v_mov_b32_e32 v1, 1
	v_mov_b32_e32 v3, 0
	s_waitcnt lgkmcnt(0)
	global_atomic_add v2, v0, v1, s[8:9] sc0
	s_min_u32 s11, s10, 8
	s_mul_i32 s11, s11, 6
	s_sub_i32 s10, s10, s0
	s_add_i32 s10, s10, 7
	s_lshr_b32 s10, s10, 3
	s_mul_i32 s10, s10, 6
	s_mov_b32 s12, 0x8000
	v_add_u32_e32 v0, 0x400, v0
	s_waitcnt vmcnt(0)
	v_readfirstlane_b32 s0, v2
	s_nop 0
	s_add_i32 s0, s0, 1
	s_cmp_lg_u32 s0, s10
	s_cbranch_scc1 .Lgsync_spin_6
	v_mov_b32_e32 v2, 0x4807c00
	global_atomic_add v2, v1, s[8:9]
	global_atomic_add v2, v1, s[8:9] offset:128
	global_atomic_add v2, v1, s[8:9] offset:256
	global_atomic_add v2, v1, s[8:9] offset:384
	global_atomic_add v2, v1, s[8:9] offset:512
	global_atomic_add v2, v1, s[8:9] offset:640
	global_atomic_add v2, v1, s[8:9] offset:768
	global_atomic_add v2, v1, s[8:9] offset:896

; __global__ void __launch_bounds__(512) mega_fwd(Params p) {
;     ...
;   grid.sync();
.LBB0_574:
	s_or_b64 exec, exec, s[6:7]
	s_waitcnt vmcnt(0) lgkmcnt(0)
	s_barrier
	s_and_saveexec_b64 s[6:7], s[94:95]
	s_cbranch_execz .LBB0_584
	buffer_wbl2 sc1
	s_waitcnt vmcnt(0)
	s_sub_u32 s8, s92, 8
	s_subb_u32 s9, s93, 0
	s_load_dword s10, s[92:93], 0x0
	s_load_dwordx2 s[8:9], s[8:9], 0x0
	s_and_b32 s0, s2, 7
	s_lshl_b32 s1, s0, 7
	s_add_i32 s1, s1, 0x4807800
	v_mov_b32_e32 v0, s1
	v_mov_b32_e32 v1, 1
	v_mov_b32_e32 v3, 0
	s_waitcnt lgkmcnt(0)
	global_atomic_add v2, v0, v1, s[8:9] sc0
	s_min_u32 s11, s10, 8
	s_mul_i32 s11, s11, 7
	s_sub_i32 s10, s10, s0
	s_add_i32 s10, s10, 7
	s_lshr_b32 s10, s10, 3
	s_mul_i32 s10, s10, 7
	s_mov_b32 s12, 0x8000
	v_add_u32_e32 v0, 0x400, v0
	s_waitcnt vmcnt(0)
	v_readfirstlane_b32 s0, v2
	s_nop 0
	s_add_i32 s0, s0, 1
	s_cmp_lg_u32 s0, s10
	s_cbranch_scc1 .Lgsync_spin_7
	v_mov_b32_e32 v2, 0x4807c00
	global_atomic_add v2, v1, s[8:9]
	global_atomic_add v2, v1, s[8:9] offset:128
	global_atomic_add v2, v1, s[8:9] offset:256
	global_atomic_add v2, v1, s[8:9] offset:384
	global_atomic_add v2, v1, s[8:9] offset:512
	global_atomic_add v2, v1, s[8:9] offset:640
	global_atomic_add v2, v1, s[8:9] offset:768
	global_atomic_add v2, v1, s[8:9] offset:896

; __global__ void __launch_bounds__(512) mega_fwd(Params p) {
;     ...
;   grid.sync();
.LBB0_635:
	s_waitcnt vmcnt(0)
	s_barrier
	s_and_saveexec_b64 s[6:7], s[94:95]
	s_cbranch_execz .LBB0_645
	buffer_wbl2 sc1
	s_waitcnt vmcnt(0)
	s_sub_u32 s8, s92, 8
	s_subb_u32 s9, s93, 0
	s_load_dword s10, s[92:93], 0x0
	s_load_dwordx2 s[8:9], s[8:9], 0x0
	s_and_b32 s0, s2, 7
	s_lshl_b32 s1, s0, 7
	s_add_i32 s1, s1, 0x4807800
	v_mov_b32_e32 v0, s1
	v_mov_b32_e32 v1, 1
	v_mov_b32_e32 v3, 0
	s_waitcnt lgkmcnt(0)
	global_atomic_add v2, v0, v1, s[8:9] sc0
	s_min_u32 s11, s10, 8
	s_mul_i32 s11, s11, 8
	s_sub_i32 s10, s10, s0
	s_add_i32 s10, s10, 7
	s_lshr_b32 s10, s10, 3
	s_mul_i32 s10, s10, 8
	s_mov_b32 s4, 0x8000
	v_add_u32_e32 v0, 0x400, v0
	s_waitcnt vmcnt(0)
	v_readfirstlane_b32 s0, v2
	s_nop 0
	s_add_i32 s0, s0, 1
	s_cmp_lg_u32 s0, s10
	s_cbranch_scc1 .Lgsync_spin_8
	v_mov_b32_e32 v2, 0x4807c00
	global_atomic_add v2, v1, s[8:9]
	global_atomic_add v2, v1, s[8:9] offset:128
	global_atomic_add v2, v1, s[8:9] offset:256
	global_atomic_add v2, v1, s[8:9] offset:384
	global_atomic_add v2, v1, s[8:9] offset:512
	global_atomic_add v2, v1, s[8:9] offset:640
	global_atomic_add v2, v1, s[8:9] offset:768
	global_atomic_add v2, v1, s[8:9] offset:896
.Lgsync_spin_8:
	global_atomic_add v2, v0, v3, s[8:9] sc0
	s_waitcnt vmcnt(0)
	v_readfirstlane_b32 s0, v2
	s_nop 0
	s_cmp_ge_u32 s0, s11
	s_cbranch_scc1 .Lgsync_done_8
	s_add_i32 s4, s4, -1
	s_cmp_eq_u32 s4, 0
	s_cbranch_scc1 .Lgsync_done_8
	s_sleep 1
	s_branch .Lgsync_spin_8
